# fused out-proj/final-norm: final grid barrier skipped in fused mode (nothing follows it)
# speedup vs baseline: 1.1194x; 1.0015x over previous
.LBB0_377:
	s_cmp_lg_u32 s78, 0
	s_cbranch_scc1 .LBB0_434
	s_waitcnt vmcnt(0)
	s_barrier
	s_mov_b64 s[0:1], exec
	v_readlane_b32 s2, v254, 1
	v_readlane_b32 s3, v254, 2
	s_and_b64 s[2:3], s[0:1], s[2:3]
	v_readlane_b32 s56, v254, 11
	v_readlane_b32 s57, v254, 12
	s_mov_b64 exec, s[2:3]
	s_cbranch_execz .LBB0_429
	s_add_i32 s2, 0, 0x20000
	v_mov_b32_e32 v0, s2
	s_waitcnt vmcnt(0) expcnt(0) lgkmcnt(0)
	ds_read_b32 v2, v0
	s_add_i32 s2, 0, 0x20004
	v_mov_b32_e32 v0, s2
	ds_read_b32 v0, v0
	v_readlane_b32 s58, v254, 14
	s_waitcnt lgkmcnt(1)
	v_cmp_ne_u32_e32 vcc, 0, v2
	v_readlane_b32 s59, v254, 15
	s_cbranch_vccnz .LBB0_393
	v_readlane_b32 s2, v254, 0
	s_mul_i32 s11, s69, s2
	s_add_u32 s2, s42, 0x60d0200
	s_addc_u32 s3, s43, 0
	s_add_u32 s4, s42, 0x60d0400
	s_addc_u32 s5, s43, 0
	s_add_u32 s6, s42, 0x60d0500
	s_addc_u32 s7, s43, 0
	s_add_u32 s8, s42, 0x60d0600
	s_addc_u32 s9, s43, 0
	s_add_u32 s16, s42, 0x60d0700
	s_addc_u32 s17, s43, 0
	s_add_u32 s18, s42, 0x60d0800
	s_addc_u32 s19, s43, 0
	s_add_u32 s20, s42, 0x60d0900
	s_addc_u32 s21, s43, 0
	s_add_u32 s22, s42, 0x60d0a00
	s_addc_u32 s23, s43, 0
	s_add_u32 s24, s42, 0x60d0b00
	s_addc_u32 s25, s43, 0
	s_add_u32 s26, s42, 0x60d0c00
	s_addc_u32 s27, s43, 0
	s_add_u32 s28, s42, 0x60d0d00
	s_addc_u32 s29, s43, 0
	s_add_u32 s30, s42, 0x60d0e00
	s_addc_u32 s31, s43, 0
	s_add_u32 s34, s42, 0x60d0f00
	s_addc_u32 s35, s43, 0
	s_add_u32 s36, s42, 0x60d1000
	s_addc_u32 s37, s43, 0
	s_add_u32 s44, s42, 0x60d1100
	s_addc_u32 s45, s43, 0
	s_add_u32 s46, s42, 0x60d1200
	s_addc_u32 s47, s43, 0
	s_add_u32 s48, s42, 0x60d1300
	s_mul_i32 s11, s11, s68
	s_addc_u32 s49, s43, 0
	s_mov_b32 s33, 1
	v_mov_b32_e32 v16, 0
	s_branch .LBB0_381
